# dilated output stores widened to 16 B via permlane32_swap; GLA output-phase norm-gain loads hoisted above the stores
# speedup vs baseline: 1.0253x; 1.0024x over previous
; #define LAS __attribute__((address_space(3)))
; DI unsigned pk2(float lo, float hi) { return cvtpk(lo, hi); }
; template <int PH>
; DI void gla_unit(LAS char* lds, int unit, const bf16* PROJ, const float* W2, const float* gb, bf16* SC, float* DEC, const float* cnorm, bf16* MIXED, bf16* QG, bf16* KG) {
;     ...
;         { const int i = tid >> 3, part = tid & 7;
;           const LAS float* orow = OF + i * 192 + 24 * part;
;           float ov[24]; float ss = 0.f;
; #pragma unroll
;           for (int j = 0; j < 24; ++j) { ov[j] = orow[j]; ss += ov[j] * ov[j]; }
;           ss += __shfl_xor(ss, 1); ss += __shfl_xor(ss, 2); ss += __shfl_xor(ss, 4);
;           const float rstd = 1.f / sqrtf(ss * (1.f / 192.f) + EPS);
;           const bf16* rcp = PROJ + (row0 + i) * PROJP + O_RC + 192 * h + 24 * part;
;           bf16* op = MIXED + (row0 + i) * D + 1280 + 192 * h + 24 * part;
;           const float* cn = cnorm + 24 * part;
; #pragma unroll
;           for (int q = 0; q < 3; ++q) { const u32x4 rv = *(const u32x4*)(rcp + 8 * q); u32x4 o;
; #pragma unroll
;               for (int e = 0; e < 4; ++e) { const float r0 = bflo(rv[e]), r1 = bfhi(rv[e]);
;                   const float y0 = ov[8 * q + 2 * e] * rstd * cn[8 * q + 2 * e] * (r0 * __builtin_amdgcn_rcpf(1.f + __expf(-r0))), y1 = ov[8 * q + 2 * e + 1] * rstd * cn[8 * q + 2 * e + 1] * (r1 * __builtin_amdgcn_rcpf(1.f + __expf(-r1)));
;                   o[e] = pk2(y0, y1); }
;               *(u32x4*)(op + 8 * q) = o; } }
.LBB0_266:
	v_mul_lo_u32 v0, v20, s13
	v_lshlrev_b32_e32 v78, 2, v21
	v_add3_u32 v34, 0, v0, v78
	v_xor_b32_e32 v0, 1, v235
	v_add_u32_e32 v6, 64, v236
	v_cmp_lt_i32_e32 vcc, v0, v6
	s_lshl_b32 s30, s30, 1
	s_waitcnt lgkmcnt(0)
	v_cndmask_b32_e32 v0, v235, v0, vcc
	v_lshlrev_b32_e32 v81, 2, v0
	v_xor_b32_e32 v0, 2, v235
	v_cmp_lt_i32_e32 vcc, v0, v6
	s_barrier
	s_nop 0
	v_cndmask_b32_e32 v0, v235, v0, vcc
	v_lshlrev_b32_e32 v80, 2, v0
	v_xor_b32_e32 v0, 4, v235
	v_cmp_lt_i32_e32 vcc, v0, v6
	v_mov_b64_e32 v[6:7], s[80:81]
	v_mad_u64_u32 v[6:7], s[4:5], v18, s0, v[6:7]
	v_cndmask_b32_e32 v0, v235, v0, vcc
	v_lshlrev_b32_e32 v79, 2, v0
	v_mov_b32_e32 v0, v7
	v_mad_u64_u32 v[8:9], s[4:5], v19, s0, v[0:1]
	v_mov_b32_e32 v7, v8
	v_lshl_add_u64 v[6:7], v[6:7], 0, s[30:31]
	v_lshlrev_b32_e32 v0, 1, v21
	v_lshl_add_u64 v[6:7], v[6:7], 0, v[0:1]
	s_mov_b64 s[4:5], 0x1810
	v_lshlrev_b64 v[8:9], 12, v[18:19]
	v_lshl_add_u64 v[10:11], v[6:7], 0, s[4:5]
	v_lshl_add_u64 v[8:9], s[96:97], 0, v[8:9]
	v_add_co_u32_e32 v6, vcc, s16, v6
	v_lshl_add_u64 v[8:9], v[8:9], 0, s[30:31]
	s_nop 0
	v_addc_co_u32_e32 v7, vcc, 0, v7, vcc
	ds_read_b128 v[2:5], v34 offset:80
	v_lshl_add_u64 v[38:39], v[8:9], 0, v[0:1]
	global_load_dwordx4 v[40:43], v[6:7], off offset:2064
	s_nop 0
	global_load_dwordx4 v[6:9], v[10:11], off offset:32
	global_load_dwordx4 v[82:85], v[10:11], off offset:16
	ds_read_b128 v[22:25], v34
	ds_read_b128 v[18:21], v34 offset:16
	ds_read_b128 v[14:17], v34 offset:32
	ds_read_b128 v[10:13], v34 offset:48
	global_load_dwordx4 v[26:29], v78, s[8:9] offset:16
	global_load_dwordx4 v[30:33], v78, s[8:9]
	global_load_dwordx4 v[88:91], v78, s[8:9] offset:48
	global_load_dwordx4 v[92:95], v78, s[8:9] offset:32
	global_load_dwordx4 v[96:99], v78, s[8:9] offset:80
	global_load_dwordx4 v[100:103], v78, s[8:9] offset:64
	s_waitcnt lgkmcnt(3)
	v_pk_mul_f32 v[70:71], v[22:23], v[22:23]
	v_pk_mul_f32 v[68:69], v[24:25], v[24:25]
	s_waitcnt lgkmcnt(2)
	v_pk_mul_f32 v[62:63], v[18:19], v[18:19]
	v_pk_mul_f32 v[60:61], v[20:21], v[20:21]
	s_waitcnt lgkmcnt(1)
	v_pk_mul_f32 v[74:75], v[14:15], v[14:15]
	v_pk_mul_f32 v[72:73], v[16:17], v[16:17]
	s_waitcnt lgkmcnt(0)
	v_pk_mul_f32 v[66:67], v[10:11], v[10:11]
	v_pk_mul_f32 v[64:65], v[12:13], v[12:13]
	v_pk_mul_f32 v[46:47], v[2:3], v[2:3]
	v_pk_mul_f32 v[44:45], v[4:5], v[4:5]
	s_mov_b32 s2, 0xf800000
	s_add_i32 s1, s1, s92
	s_cmpk_gt_i32 s1, 0x7ff
	s_waitcnt vmcnt(8)
	v_lshlrev_b32_e32 v36, 16, v42
	v_mul_f32_e32 v0, 0xbfb8aa3b, v36
	v_exp_f32_e32 v0, v0
	v_and_b32_e32 v37, 0xffff0000, v42
	s_waitcnt vmcnt(7)
	v_lshlrev_b32_e32 v76, 16, v6
	v_and_b32_e32 v77, 0xffff0000, v6
	v_add_f32_e32 v0, 1.0, v0
	v_rcp_f32_e32 v48, v0
	v_mul_f32_e32 v0, 0xbfb8aa3b, v37
	v_exp_f32_e32 v0, v0
	s_nop 0
	v_add_f32_e32 v0, 1.0, v0
	v_rcp_f32_e32 v49, v0
	s_nop 0
	v_pk_mul_f32 v[52:53], v[48:49], v[36:37]
	v_lshlrev_b32_e32 v36, 16, v41
	v_mul_f32_e32 v0, 0xbfb8aa3b, v36
	v_exp_f32_e32 v0, v0
	v_and_b32_e32 v37, 0xffff0000, v41
	v_add_f32_e32 v0, 1.0, v0
	v_rcp_f32_e32 v48, v0
	v_mul_f32_e32 v0, 0xbfb8aa3b, v37
	v_exp_f32_e32 v0, v0
	s_nop 0
	v_add_f32_e32 v0, 1.0, v0
	v_rcp_f32_e32 v49, v0
	s_nop 0
	v_pk_mul_f32 v[54:55], v[48:49], v[36:37]
	v_lshlrev_b32_e32 v36, 16, v40
	v_mul_f32_e32 v0, 0xbfb8aa3b, v36
	v_exp_f32_e32 v0, v0
	v_and_b32_e32 v37, 0xffff0000, v40
	v_add_f32_e32 v0, 1.0, v0
	v_rcp_f32_e32 v40, v0
	v_mul_f32_e32 v0, 0xbfb8aa3b, v37
	v_exp_f32_e32 v0, v0
	s_nop 0
	v_add_f32_e32 v0, 1.0, v0
	v_rcp_f32_e32 v41, v0
	s_nop 0
	v_pk_mul_f32 v[58:59], v[40:41], v[36:37]
	v_lshlrev_b32_e32 v36, 16, v43
	v_mul_f32_e32 v0, 0xbfb8aa3b, v36
	v_exp_f32_e32 v0, v0
	v_and_b32_e32 v37, 0xffff0000, v43
	v_add_f32_e32 v0, 1.0, v0
	v_rcp_f32_e32 v40, v0
	v_mul_f32_e32 v0, 0xbfb8aa3b, v37
	v_exp_f32_e32 v0, v0
	s_nop 0
	v_add_f32_e32 v0, 1.0, v0
	v_rcp_f32_e32 v41, v0
	s_nop 0
	v_pk_mul_f32 v[56:57], v[40:41], v[36:37]
	s_waitcnt vmcnt(6)
	v_lshlrev_b32_e32 v36, 16, v84
	v_mul_f32_e32 v0, 0xbfb8aa3b, v36
	v_exp_f32_e32 v0, v0
	v_and_b32_e32 v37, 0xffff0000, v84
	v_add_f32_e32 v0, 1.0, v0
	v_rcp_f32_e32 v40, v0
	v_mul_f32_e32 v0, 0xbfb8aa3b, v37
	v_exp_f32_e32 v0, v0
	s_nop 0
	v_add_f32_e32 v0, 1.0, v0
	v_rcp_f32_e32 v41, v0
	s_nop 0
	v_pk_mul_f32 v[40:41], v[40:41], v[36:37]
	v_lshlrev_b32_e32 v36, 16, v83
	v_mul_f32_e32 v0, 0xbfb8aa3b, v36
	v_exp_f32_e32 v0, v0
	v_and_b32_e32 v37, 0xffff0000, v83
	v_add_f32_e32 v0, 1.0, v0
	v_rcp_f32_e32 v42, v0
	v_mul_f32_e32 v0, 0xbfb8aa3b, v37
	v_exp_f32_e32 v0, v0
	s_nop 0
	v_add_f32_e32 v0, 1.0, v0
	v_rcp_f32_e32 v43, v0
	s_nop 0
	v_pk_mul_f32 v[42:43], v[42:43], v[36:37]
	v_lshlrev_b32_e32 v36, 16, v82
	v_mul_f32_e32 v0, 0xbfb8aa3b, v36
	v_exp_f32_e32 v0, v0
	v_and_b32_e32 v37, 0xffff0000, v82
	v_add_f32_e32 v0, 1.0, v0
	v_rcp_f32_e32 v48, v0
	v_mul_f32_e32 v0, 0xbfb8aa3b, v37
	v_exp_f32_e32 v0, v0
	s_nop 0
	v_add_f32_e32 v0, 1.0, v0
	v_rcp_f32_e32 v49, v0
	s_nop 0
	v_pk_mul_f32 v[50:51], v[48:49], v[36:37]
	v_lshlrev_b32_e32 v36, 16, v85
	v_mul_f32_e32 v0, 0xbfb8aa3b, v36
	v_exp_f32_e32 v0, v0
	v_and_b32_e32 v37, 0xffff0000, v85
	v_add_f32_e32 v0, 1.0, v0
	v_rcp_f32_e32 v48, v0
	v_mul_f32_e32 v0, 0xbfb8aa3b, v37
	v_exp_f32_e32 v0, v0
	s_nop 0
	v_add_f32_e32 v0, 1.0, v0
	v_rcp_f32_e32 v49, v0
	v_mul_f32_e32 v0, 0xbfb8aa3b, v76
	v_exp_f32_e32 v0, v0
	v_pk_mul_f32 v[48:49], v[48:49], v[36:37]
	ds_read_b128 v[34:37], v34 offset:64
	v_add_f32_e32 v0, 1.0, v0
	v_rcp_f32_e32 v86, v0
	v_mul_f32_e32 v0, 0xbfb8aa3b, v77
	v_exp_f32_e32 v0, v0
	s_waitcnt lgkmcnt(0)
; DI unsigned pk2(float lo, float hi) { return cvtpk(lo, hi); }
; template <int PH>
; DI void gla_unit(LAS char* lds, int unit, const bf16* PROJ, const float* W2, const float* gb, bf16* SC, float* DEC, const float* cnorm, bf16* MIXED, bf16* QG, bf16* KG) {
;     ...
;           ss += __shfl_xor(ss, 1); ss += __shfl_xor(ss, 2); ss += __shfl_xor(ss, 4);
;           const float rstd = 1.f / sqrtf(ss * (1.f / 192.f) + EPS);
;           const bf16* rcp = PROJ + (row0 + i) * PROJP + O_RC + 192 * h + 24 * part;
;           bf16* op = MIXED + (row0 + i) * D + 1280 + 192 * h + 24 * part;
;           const float* cn = cnorm + 24 * part;
; #pragma unroll
;           for (int q = 0; q < 3; ++q) { const u32x4 rv = *(const u32x4*)(rcp + 8 * q); u32x4 o;
; #pragma unroll
;               for (int e = 0; e < 4; ++e) { const float r0 = bflo(rv[e]), r1 = bfhi(rv[e]);
;                   const float y0 = ov[8 * q + 2 * e] * rstd * cn[8 * q + 2 * e] * (r0 * __builtin_amdgcn_rcpf(1.f + __expf(-r0))), y1 = ov[8 * q + 2 * e + 1] * rstd * cn[8 * q + 2 * e + 1] * (r1 * __builtin_amdgcn_rcpf(1.f + __expf(-r1)));
;                   o[e] = pk2(y0, y1); }
;               *(u32x4*)(op + 8 * q) = o; } }
	v_pk_mul_f32 v[84:85], v[34:35], v[34:35]
	v_pk_mul_f32 v[82:83], v[36:37], v[36:37]
	v_add_f32_e32 v0, 1.0, v0
	v_rcp_f32_e32 v87, v0
	v_add_f32_e32 v0, v70, v71
	v_add_f32_e32 v0, v0, v68
	v_add_f32_e32 v0, v0, v69
	v_add_f32_e32 v0, v0, v62
	v_add_f32_e32 v0, v0, v63
	v_add_f32_e32 v0, v0, v60
	v_add_f32_e32 v0, v0, v61
	v_add_f32_e32 v0, v0, v74
	v_add_f32_e32 v0, v0, v75
	v_add_f32_e32 v0, v0, v72
	v_add_f32_e32 v0, v0, v73
	v_add_f32_e32 v0, v0, v66
	v_add_f32_e32 v0, v0, v67
	v_add_f32_e32 v0, v0, v64
	v_add_f32_e32 v0, v0, v65
	v_add_f32_e32 v0, v0, v84
	v_add_f32_e32 v0, v0, v85
	v_add_f32_e32 v0, v0, v82
	v_add_f32_e32 v0, v0, v83
	v_add_f32_e32 v0, v0, v46
	v_add_f32_e32 v0, v0, v47
	v_add_f32_e32 v0, v0, v44
	v_add_f32_e32 v0, v0, v45
	ds_bpermute_b32 v6, v81, v0
	v_pk_mul_f32 v[76:77], v[86:87], v[76:77]
	s_waitcnt lgkmcnt(0)
	v_add_f32_e32 v0, v0, v6
	ds_bpermute_b32 v6, v80, v0
	s_waitcnt lgkmcnt(0)
	v_add_f32_e32 v0, v0, v6
	ds_bpermute_b32 v6, v79, v0
	s_waitcnt lgkmcnt(0)
	v_add_f32_e32 v0, v0, v6
	v_fmamk_f32 v0, v0, 0x3baaaaab, v232
	v_cmp_gt_f32_e32 vcc, s2, v0
	v_mul_f32_e32 v6, 0x4f800000, v0
	s_nop 0
	v_cndmask_b32_e32 v0, v0, v6, vcc
	v_sqrt_f32_e32 v6, v0
	s_nop 0
	v_add_u32_e32 v44, -1, v6
	v_fma_f32 v45, -v44, v6, v0
	v_cmp_ge_f32_e64 s[40:41], 0, v45
	v_add_u32_e32 v45, 1, v6
	s_nop 0
	v_cndmask_b32_e64 v44, v6, v44, s[40:41]
	v_fma_f32 v6, -v45, v6, v0
	v_cmp_lt_f32_e64 s[40:41], 0, v6
	s_nop 1
	v_cndmask_b32_e64 v6, v44, v45, s[40:41]
	v_mul_f32_e32 v44, 0x37800000, v6
	v_cndmask_b32_e32 v6, v6, v44, vcc
	v_cmp_class_f32_e32 vcc, v0, v233
	s_nop 1
	v_cndmask_b32_e32 v0, v6, v0, vcc
	v_div_scale_f32 v6, s[4:5], v0, v0, 1.0
	v_rcp_f32_e32 v44, v6
	s_nop 0
	v_fma_f32 v45, -v6, v44, 1.0
	v_fmac_f32_e32 v44, v45, v44
	v_div_scale_f32 v45, vcc, 1.0, v0, 1.0
	v_mul_f32_e32 v46, v45, v44
	v_fma_f32 v47, -v6, v46, v45
	v_fmac_f32_e32 v46, v47, v44
	v_fma_f32 v6, -v6, v46, v45
	v_div_fmas_f32 v6, v6, v44, v46
	v_div_fixup_f32 v0, v6, v0, 1.0
	v_pk_mul_f32 v[22:23], v[22:23], v[0:1] op_sel_hi:[1,0]
	v_pk_mul_f32 v[24:25], v[24:25], v[0:1] op_sel_hi:[1,0]
	v_pk_mul_f32 v[18:19], v[18:19], v[0:1] op_sel_hi:[1,0]
	s_waitcnt vmcnt(0)
	v_pk_mul_f32 v[22:23], v[30:31], v[22:23]
	v_pk_mul_f32 v[24:25], v[32:33], v[24:25]
	v_pk_mul_f32 v[18:19], v[26:27], v[18:19]
	v_pk_mul_f32 v[22:23], v[22:23], v[58:59]
	v_pk_mul_f32 v[24:25], v[24:25], v[54:55]
	v_pk_mul_f32 v[18:19], v[18:19], v[52:53]
	v_cvt_pk_bf16_f32 v22, v22, v23
	v_cvt_pk_bf16_f32 v23, v24, v25
	v_cvt_pk_bf16_f32 v24, v18, v19
	v_pk_mul_f32 v[18:19], v[20:21], v[0:1] op_sel_hi:[1,0]
	v_pk_mul_f32 v[14:15], v[14:15], v[0:1] op_sel_hi:[1,0]
	v_pk_mul_f32 v[18:19], v[18:19], v[28:29]
	v_pk_mul_f32 v[16:17], v[16:17], v[0:1] op_sel_hi:[1,0]
	v_pk_mul_f32 v[18:19], v[56:57], v[18:19]
	v_pk_mul_f32 v[10:11], v[10:11], v[0:1] op_sel_hi:[1,0]
	v_cvt_pk_bf16_f32 v25, v18, v19
	global_store_dwordx4 v[38:39], v[22:25], off offset:2560
	s_nop 1
	v_mov_b32_e32 v18, v88
	v_mov_b32_e32 v19, v89
	v_mov_b32_e32 v20, v90
	v_mov_b32_e32 v21, v91
	v_mov_b32_e32 v22, v92
	v_mov_b32_e32 v23, v93
	v_mov_b32_e32 v24, v94
	v_mov_b32_e32 v25, v95
	v_pk_mul_f32 v[2:3], v[2:3], v[0:1] op_sel_hi:[1,0]
	v_pk_mul_f32 v[4:5], v[4:5], v[0:1] op_sel_hi:[1,0]
	s_nop 0
	v_pk_mul_f32 v[10:11], v[10:11], v[18:19]
	s_nop 0
	v_pk_mul_f32 v[14:15], v[14:15], v[22:23]
	v_pk_mul_f32 v[16:17], v[16:17], v[24:25]
	v_pk_mul_f32 v[14:15], v[14:15], v[50:51]
	v_pk_mul_f32 v[16:17], v[16:17], v[42:43]
	v_pk_mul_f32 v[10:11], v[10:11], v[40:41]
	v_cvt_pk_bf16_f32 v14, v14, v15
	v_cvt_pk_bf16_f32 v15, v16, v17
	v_cvt_pk_bf16_f32 v16, v10, v11
	v_pk_mul_f32 v[10:11], v[12:13], v[0:1] op_sel_hi:[1,0]
	v_pk_mul_f32 v[18:19], v[34:35], v[0:1] op_sel_hi:[1,0]
	v_pk_mul_f32 v[10:11], v[10:11], v[20:21]
	v_pk_mul_f32 v[20:21], v[36:37], v[0:1] op_sel_hi:[1,0]
	v_pk_mul_f32 v[10:11], v[48:49], v[10:11]
	s_nop 0
	v_cvt_pk_bf16_f32 v17, v10, v11
	global_store_dwordx4 v[38:39], v[14:17], off offset:2576
	s_nop 1
	v_mov_b32_e32 v10, v96
	v_mov_b32_e32 v11, v97
	v_mov_b32_e32 v12, v98
	v_mov_b32_e32 v13, v99
	v_mov_b32_e32 v14, v100
	v_mov_b32_e32 v15, v101
	v_mov_b32_e32 v16, v102
	v_mov_b32_e32 v17, v103
	s_nop 0
	v_pk_mul_f32 v[2:3], v[2:3], v[10:11]
	s_nop 0
	v_pk_mul_f32 v[14:15], v[18:19], v[14:15]
	v_pk_mul_f32 v[16:17], v[20:21], v[16:17]
	v_pk_mul_f32 v[14:15], v[14:15], v[76:77]
	v_pk_mul_f32 v[4:5], v[4:5], v[12:13]
	v_cvt_pk_bf16_f32 v6, v14, v15
	v_lshlrev_b32_e32 v14, 16, v7
	v_and_b32_e32 v15, 0xffff0000, v7
	v_mul_f32_e32 v7, 0xbfb8aa3b, v14
	v_exp_f32_e32 v7, v7
	s_nop 0
	v_add_f32_e32 v7, 1.0, v7
	v_rcp_f32_e32 v18, v7
	v_mul_f32_e32 v7, 0xbfb8aa3b, v15
	v_exp_f32_e32 v7, v7
	s_nop 0
	v_add_f32_e32 v7, 1.0, v7
	v_rcp_f32_e32 v19, v7
	s_nop 0
	v_pk_mul_f32 v[14:15], v[18:19], v[14:15]
	s_nop 0
	v_pk_mul_f32 v[14:15], v[16:17], v[14:15]
	s_nop 0
	v_cvt_pk_bf16_f32 v7, v14, v15
	v_lshlrev_b32_e32 v14, 16, v8
	v_and_b32_e32 v15, 0xffff0000, v8
	v_mul_f32_e32 v8, 0xbfb8aa3b, v14
	v_exp_f32_e32 v8, v8
	s_nop 0
	v_add_f32_e32 v8, 1.0, v8
	v_rcp_f32_e32 v16, v8
	v_mul_f32_e32 v8, 0xbfb8aa3b, v15
	v_exp_f32_e32 v8, v8
	s_nop 0
	v_add_f32_e32 v8, 1.0, v8
	v_rcp_f32_e32 v17, v8
	s_nop 0
	v_pk_mul_f32 v[10:11], v[16:17], v[14:15]
	s_nop 0
	v_pk_mul_f32 v[2:3], v[2:3], v[10:11]
	s_nop 0
	v_cvt_pk_bf16_f32 v8, v2, v3
	v_lshlrev_b32_e32 v2, 16, v9
	v_and_b32_e32 v3, 0xffff0000, v9
	v_mul_f32_e32 v9, 0xbfb8aa3b, v2
	v_mul_f32_e32 v0, 0xbfb8aa3b, v3
	v_exp_f32_e32 v9, v9
	v_exp_f32_e32 v0, v0
	v_add_f32_e32 v9, 1.0, v9
	v_add_f32_e32 v0, 1.0, v0
	v_rcp_f32_e32 v10, v9
	v_rcp_f32_e32 v11, v0
	s_nop 0
	v_pk_mul_f32 v[2:3], v[10:11], v[2:3]
	s_nop 0
	v_pk_mul_f32 v[2:3], v[2:3], v[4:5]
	s_nop 0
	v_cvt_pk_bf16_f32 v9, v2, v3
	global_store_dwordx4 v[38:39], v[6:9], off offset:2592
	s_barrier
	s_cbranch_scc1 .LBB0_282

; #define DIL_LWRITE(RG) do { _Pragma("unroll") for (int i_ = 0; i_ < 6; ++i_) { const int c_ = tid + NTHR * i_, row_ = c_ >> 3, ch_ = c_ & 7; \
;         *(LAS u32x4*)(lds + DIL_KB + row_ * DIL_PITCH + 16 * ch_) = RG.k[i_]; *(LAS u32x4*)(lds + DIL_VB + row_ * DIL_PITCH + 16 * ch_) = RG.v[i_]; } } while (0)
; __global__ void __launch_bounds__(NTHR, 2) fwd_mega(Args args) {
;     ...
;                     DIL_LWRITE(RG);
;                     bf16x8 qf[4];
; #pragma unroll
;                     for (int d0 = 0; d0 < 4; ++d0) qf[d0] = RG.q[d0];
;                     __syncthreads();
;                     if (has_next) { DIL_MAKE(nxt, u + G); DIL_GLOAD(nxt, RG); }
;                     dil_compute(lds, cur, DIL_TBLP(u), tid, qf);
;                     asm volatile("s_waitcnt lgkmcnt(0)\n\ts_barrier" ::: "memory");
;                     cur = nxt; ++it;
.LBB0_521:
	s_or_b64 exec, exec, s[10:11]
	s_waitcnt lgkmcnt(0)
	s_barrier
	s_waitcnt vmcnt(4)
	v_mov_b64_e32 v[98:99], v[126:127]
	s_waitcnt vmcnt(4)
	v_mov_b64_e32 v[102:103], v[122:123]
	s_waitcnt vmcnt(4)
	v_mov_b64_e32 v[106:107], v[118:119]
	s_waitcnt vmcnt(4)
	v_mov_b64_e32 v[110:111], v[114:115]
	s_and_b64 vcc, exec, s[14:15]
	v_mov_b64_e32 v[100:101], v[128:129]
	v_mov_b64_e32 v[104:105], v[124:125]
	v_mov_b64_e32 v[108:109], v[120:121]
	v_mov_b64_e32 v[112:113], v[116:117]
	s_mov_b32 s20, s7
	s_mov_b64 s[12:13], s[16:17]
	s_mov_b64 s[8:9], s[22:23]
	s_mov_b32 s6, s26
	s_mov_b32 s5, s27
	s_mov_b32 s4, s21
	s_cbranch_vccnz .LBB0_546

; #define MFMA32(a, b, c) __builtin_amdgcn_mfma_f32_32x32x16_bf16((a), (b), (c), 0, 0, 0)
; DI bf16x8 pack8(const f32x16& x, int s) { u32x4 p; p[0] = cvtpk(x[8 * s], x[8 * s + 1]); p[1] = cvtpk(x[8 * s + 2], x[8 * s + 3]); p[2] = cvtpk(x[8 * s + 4], x[8 * s + 5]); p[3] = cvtpk(x[8 * s + 6], x[8 * s + 7]); return __builtin_bit_cast(bf16x8, p); }
; DI void dil_compute(LAS char* lds, const DilU& u, const LAS float* tbl, int tid, const bf16x8 (&qf)[4]) {
;     ...
;         float mx = p[0];
; #pragma unroll
;         for (int r = 1; r < 16; ++r) mx = fmaxf(mx, p[r]);
;         mx = fmaxf(mx, __shfl_xor(mx, 32));
;         const float mn = fmaxf(m, mx);
;         if (__any(mn > m)) {
;             const float mr_ = (mn == -INFINITY) ? 0.f : mn;
;             const float alpha = __builtin_amdgcn_exp2f(m - mr_);
;             l *= alpha;
; #pragma unroll
;             for (int i = 0; i < 2; ++i)
; #pragma unroll
;                 for (int r = 0; r < 16; ++r) o[i][r] *= alpha;
;             m = mn;
;         }
;         const float mref = (m == -INFINITY) ? 0.f : m;
; #pragma unroll
;         for (int r = 0; r < 16; ++r) { p[r] = __builtin_amdgcn_exp2f(p[r] - mref); l += p[r]; }
;         const bf16x8 pb0 = pack8(p, 0), pb1 = pack8(p, 1);
; #pragma unroll
;         for (int db = 0; db < 2; ++db) {
;             const bf16x8 v0 = frag_tr_perm(Vt, DIL_PITCH, 0, 32 * db, lane), v1 = frag_tr_perm(Vt, DIL_PITCH, 16, 32 * db, lane);
;             o[db] = MFMA32(v0, pb0, o[db]); o[db] = MFMA32(v1, pb1, o[db]);
;         }
.Ldil_nomask:
	v_max3_f32 v145, v170, v171, v220
	v_max3_f32 v145, v145, v221, v223
	ds_bpermute_b32 v222, v133, v145
	v_mov_b32_e32 v221, 0xff800000
	s_waitcnt lgkmcnt(0)
	v_max_f32_e32 v145, v145, v222
	v_cmp_neq_f32_e32 vcc, v145, v221
	s_nop 1
	v_cndmask_b32_e32 v170, 0, v145, vcc
	v_sub_f32_e32 v172, v172, v170
	v_sub_f32_e32 v173, v173, v170
	v_sub_f32_e32 v174, v174, v170
	v_sub_f32_e32 v175, v175, v170
	v_sub_f32_e32 v176, v176, v170
	v_sub_f32_e32 v177, v177, v170
	v_sub_f32_e32 v178, v178, v170
	v_sub_f32_e32 v179, v179, v170
	v_sub_f32_e32 v180, v180, v170
	v_sub_f32_e32 v181, v181, v170
	v_sub_f32_e32 v182, v182, v170
	v_sub_f32_e32 v183, v183, v170
	v_sub_f32_e32 v184, v184, v170
	v_sub_f32_e32 v185, v185, v170
	v_sub_f32_e32 v186, v186, v170
	v_sub_f32_e32 v187, v187, v170
	v_exp_f32_e32 v172, v172
	v_exp_f32_e32 v173, v173
	v_exp_f32_e32 v174, v174
	v_exp_f32_e32 v175, v175
	v_exp_f32_e32 v176, v176
	v_exp_f32_e32 v177, v177
	v_exp_f32_e32 v178, v178
	v_exp_f32_e32 v179, v179
	v_exp_f32_e32 v180, v180
	v_exp_f32_e32 v181, v181
	v_exp_f32_e32 v182, v182
	v_exp_f32_e32 v183, v183
	v_exp_f32_e32 v184, v184
	v_exp_f32_e32 v185, v185
	v_exp_f32_e32 v186, v186
	v_exp_f32_e32 v187, v187
	v_add_f32_e32 v171, v172, v174
	v_add_f32_e32 v220, v173, v175
	v_add_f32_e32 v171, v171, v176
	v_add_f32_e32 v220, v220, v177
	v_add_f32_e32 v171, v171, v178
	v_add_f32_e32 v220, v220, v179
	v_add_f32_e32 v171, v171, v180
	v_add_f32_e32 v220, v220, v181
	v_add_f32_e32 v171, v171, v182
	v_add_f32_e32 v220, v220, v183
	v_add_f32_e32 v171, v171, v184
	v_add_f32_e32 v220, v220, v185
	v_add_f32_e32 v171, v171, v186
	v_add_f32_e32 v220, v220, v187
	v_cvt_pk_bf16_f32 v98, v172, v173
	v_cvt_pk_bf16_f32 v99, v174, v175
	v_cvt_pk_bf16_f32 v100, v176, v177
	v_cvt_pk_bf16_f32 v101, v178, v179
	v_cvt_pk_bf16_f32 v102, v180, v181
	v_cvt_pk_bf16_f32 v103, v182, v183
	v_cvt_pk_bf16_f32 v104, v184, v185
	v_cvt_pk_bf16_f32 v105, v186, v187
	v_add_u32_e32 v222, 0, v153
	ds_read_b64_tr_b16 v[172:173], v222 offset:55296
	ds_read_b64_tr_b16 v[174:175], v222 offset:56448
	ds_read_b64_tr_b16 v[176:177], v222 offset:57600
	ds_read_b64_tr_b16 v[178:179], v222 offset:58752
	ds_read_b64_tr_b16 v[180:181], v222 offset:55360
	ds_read_b64_tr_b16 v[182:183], v222 offset:56512
	ds_read_b64_tr_b16 v[184:185], v222 offset:57664
	ds_read_b64_tr_b16 v[186:187], v222 offset:58816
	v_sub_f32_e32 v188, v188, v170
	v_sub_f32_e32 v189, v189, v170
	v_sub_f32_e32 v190, v190, v170
	v_sub_f32_e32 v191, v191, v170
	v_sub_f32_e32 v192, v192, v170
	v_sub_f32_e32 v193, v193, v170
	v_sub_f32_e32 v194, v194, v170
	v_sub_f32_e32 v195, v195, v170
	v_sub_f32_e32 v196, v196, v170
	v_sub_f32_e32 v197, v197, v170
	v_sub_f32_e32 v198, v198, v170
	v_sub_f32_e32 v199, v199, v170
	v_sub_f32_e32 v200, v200, v170
	v_sub_f32_e32 v201, v201, v170
	v_sub_f32_e32 v202, v202, v170
	v_sub_f32_e32 v203, v203, v170
	v_exp_f32_e32 v188, v188
	v_exp_f32_e32 v189, v189
	v_exp_f32_e32 v190, v190
	v_exp_f32_e32 v191, v191
	v_exp_f32_e32 v192, v192
	v_exp_f32_e32 v193, v193
	v_exp_f32_e32 v194, v194
	v_exp_f32_e32 v195, v195
	v_exp_f32_e32 v196, v196
	v_exp_f32_e32 v197, v197
	v_exp_f32_e32 v198, v198
	v_exp_f32_e32 v199, v199
	v_exp_f32_e32 v200, v200
	v_exp_f32_e32 v201, v201
	v_exp_f32_e32 v202, v202
	v_exp_f32_e32 v203, v203
	v_add_f32_e32 v171, v171, v188
	v_add_f32_e32 v220, v220, v189
	v_add_f32_e32 v171, v171, v190
	v_add_f32_e32 v220, v220, v191
	v_add_f32_e32 v171, v171, v192
	v_add_f32_e32 v220, v220, v193
	v_add_f32_e32 v171, v171, v194
	v_add_f32_e32 v220, v220, v195
	v_add_f32_e32 v171, v171, v196
	v_add_f32_e32 v220, v220, v197
	v_add_f32_e32 v171, v171, v198
	v_add_f32_e32 v220, v220, v199
	v_add_f32_e32 v171, v171, v200
	v_add_f32_e32 v220, v220, v201
	v_add_f32_e32 v171, v171, v202
	v_add_f32_e32 v220, v220, v203
	v_cvt_pk_bf16_f32 v106, v188, v189
	v_cvt_pk_bf16_f32 v107, v190, v191
	v_cvt_pk_bf16_f32 v108, v192, v193
	v_cvt_pk_bf16_f32 v109, v194, v195
	v_cvt_pk_bf16_f32 v110, v196, v197
	v_cvt_pk_bf16_f32 v111, v198, v199
	v_cvt_pk_bf16_f32 v112, v200, v201
	v_cvt_pk_bf16_f32 v113, v202, v203
	s_waitcnt lgkmcnt(6)
	v_mfma_f32_32x32x16_bf16 v[18:33], v[172:175], v[98:101], 0
	s_waitcnt lgkmcnt(4)
	v_mfma_f32_32x32x16_bf16 v[18:33], v[176:179], v[102:105], v[18:33]
	s_waitcnt lgkmcnt(2)
	v_mfma_f32_32x32x16_bf16 v[2:17], v[180:183], v[98:101], 0
	s_waitcnt lgkmcnt(0)
	v_mfma_f32_32x32x16_bf16 v[2:17], v[184:187], v[102:105], v[2:17]
	v_add_u32_e32 v222, 4608, v153
	ds_read_b64_tr_b16 v[188:189], v222 offset:55296
	ds_read_b64_tr_b16 v[190:191], v222 offset:56448
	ds_read_b64_tr_b16 v[192:193], v222 offset:57600
	ds_read_b64_tr_b16 v[194:195], v222 offset:58752
	ds_read_b64_tr_b16 v[196:197], v222 offset:55360
	ds_read_b64_tr_b16 v[198:199], v222 offset:56512
	ds_read_b64_tr_b16 v[200:201], v222 offset:57664
	ds_read_b64_tr_b16 v[202:203], v222 offset:58816
	v_sub_f32_e32 v204, v204, v170
	v_sub_f32_e32 v205, v205, v170
	v_sub_f32_e32 v206, v206, v170
	v_sub_f32_e32 v207, v207, v170
	v_sub_f32_e32 v208, v208, v170
	v_sub_f32_e32 v209, v209, v170
	v_sub_f32_e32 v210, v210, v170
	v_sub_f32_e32 v211, v211, v170
	v_sub_f32_e32 v212, v212, v170
	v_sub_f32_e32 v213, v213, v170
	v_sub_f32_e32 v214, v214, v170
	v_sub_f32_e32 v215, v215, v170
	v_sub_f32_e32 v216, v216, v170
	v_sub_f32_e32 v217, v217, v170
	v_sub_f32_e32 v218, v218, v170
	v_sub_f32_e32 v219, v219, v170
	v_exp_f32_e32 v204, v204
	v_exp_f32_e32 v205, v205
	v_exp_f32_e32 v206, v206
	v_exp_f32_e32 v207, v207
	v_exp_f32_e32 v208, v208
	v_exp_f32_e32 v209, v209
	v_exp_f32_e32 v210, v210
	v_exp_f32_e32 v211, v211
	v_exp_f32_e32 v212, v212
	v_exp_f32_e32 v213, v213
	v_exp_f32_e32 v214, v214
	v_exp_f32_e32 v215, v215
	v_exp_f32_e32 v216, v216
	v_exp_f32_e32 v217, v217
	v_exp_f32_e32 v218, v218
	v_exp_f32_e32 v219, v219
	v_add_f32_e32 v171, v171, v204
	v_add_f32_e32 v220, v220, v205
	v_add_f32_e32 v171, v171, v206
	v_add_f32_e32 v220, v220, v207
	v_add_f32_e32 v171, v171, v208
	v_add_f32_e32 v220, v220, v209
	v_add_f32_e32 v171, v171, v210
	v_add_f32_e32 v220, v220, v211
	v_add_f32_e32 v171, v171, v212
	v_add_f32_e32 v220, v220, v213
	v_add_f32_e32 v171, v171, v214
	v_add_f32_e32 v220, v220, v215
	v_add_f32_e32 v171, v171, v216
	v_add_f32_e32 v220, v220, v217
	v_add_f32_e32 v171, v171, v218
	v_add_f32_e32 v220, v220, v219
	v_cvt_pk_bf16_f32 v98, v204, v205
	v_cvt_pk_bf16_f32 v99, v206, v207
	v_cvt_pk_bf16_f32 v100, v208, v209
	v_cvt_pk_bf16_f32 v101, v210, v211
	v_cvt_pk_bf16_f32 v102, v212, v213
	v_cvt_pk_bf16_f32 v103, v214, v215
	v_cvt_pk_bf16_f32 v104, v216, v217
	v_cvt_pk_bf16_f32 v105, v218, v219
	s_waitcnt lgkmcnt(6)
; #define MFMA32(a, b, c) __builtin_amdgcn_mfma_f32_32x32x16_bf16((a), (b), (c), 0, 0, 0)
; DI bf16x8 pack8(const f32x16& x, int s) { u32x4 p; p[0] = cvtpk(x[8 * s], x[8 * s + 1]); p[1] = cvtpk(x[8 * s + 2], x[8 * s + 3]); p[2] = cvtpk(x[8 * s + 4], x[8 * s + 5]); p[3] = cvtpk(x[8 * s + 6], x[8 * s + 7]); return __builtin_bit_cast(bf16x8, p); }
; DI void dil_compute(LAS char* lds, const DilU& u, const LAS float* tbl, int tid, const bf16x8 (&qf)[4]) {
;     ...
; #pragma unroll
;         for (int r = 0; r < 16; ++r) { p[r] = __builtin_amdgcn_exp2f(p[r] - mref); l += p[r]; }
;         const bf16x8 pb0 = pack8(p, 0), pb1 = pack8(p, 1);
; #pragma unroll
;         for (int db = 0; db < 2; ++db) {
;             const bf16x8 v0 = frag_tr_perm(Vt, DIL_PITCH, 0, 32 * db, lane), v1 = frag_tr_perm(Vt, DIL_PITCH, 16, 32 * db, lane);
;             o[db] = MFMA32(v0, pb0, o[db]); o[db] = MFMA32(v1, pb1, o[db]);
;         }
	v_mfma_f32_32x32x16_bf16 v[18:33], v[188:191], v[106:109], v[18:33]
	s_waitcnt lgkmcnt(4)
	v_mfma_f32_32x32x16_bf16 v[18:33], v[192:195], v[110:113], v[18:33]
	s_waitcnt lgkmcnt(2)
	v_mfma_f32_32x32x16_bf16 v[2:17], v[196:199], v[106:109], v[2:17]
	s_waitcnt lgkmcnt(0)
	v_mfma_f32_32x32x16_bf16 v[2:17], v[200:203], v[110:113], v[2:17]
	v_add_u32_e32 v222, 9216, v153
	ds_read_b64_tr_b16 v[204:205], v222 offset:55296
	ds_read_b64_tr_b16 v[206:207], v222 offset:56448
	ds_read_b64_tr_b16 v[208:209], v222 offset:57600
	ds_read_b64_tr_b16 v[210:211], v222 offset:58752
	ds_read_b64_tr_b16 v[212:213], v222 offset:55360
	ds_read_b64_tr_b16 v[214:215], v222 offset:56512
	ds_read_b64_tr_b16 v[216:217], v222 offset:57664
	ds_read_b64_tr_b16 v[218:219], v222 offset:58816
	v_sub_f32_e32 v154, v154, v170
	v_sub_f32_e32 v155, v155, v170
	v_sub_f32_e32 v156, v156, v170
	v_sub_f32_e32 v157, v157, v170
	v_sub_f32_e32 v158, v158, v170
	v_sub_f32_e32 v159, v159, v170
	v_sub_f32_e32 v160, v160, v170
	v_sub_f32_e32 v161, v161, v170
	v_sub_f32_e32 v162, v162, v170
	v_sub_f32_e32 v163, v163, v170
	v_sub_f32_e32 v164, v164, v170
	v_sub_f32_e32 v165, v165, v170
	v_sub_f32_e32 v166, v166, v170
	v_sub_f32_e32 v167, v167, v170
	v_sub_f32_e32 v168, v168, v170
	v_sub_f32_e32 v169, v169, v170
	v_exp_f32_e32 v154, v154
	v_exp_f32_e32 v155, v155
	v_exp_f32_e32 v156, v156
	v_exp_f32_e32 v157, v157
	v_exp_f32_e32 v158, v158
	v_exp_f32_e32 v159, v159
	v_exp_f32_e32 v160, v160
	v_exp_f32_e32 v161, v161
	v_exp_f32_e32 v162, v162
	v_exp_f32_e32 v163, v163
	v_exp_f32_e32 v164, v164
	v_exp_f32_e32 v165, v165
	v_exp_f32_e32 v166, v166
	v_exp_f32_e32 v167, v167
	v_exp_f32_e32 v168, v168
	v_exp_f32_e32 v169, v169
	v_add_f32_e32 v171, v171, v154
	v_add_f32_e32 v220, v220, v155
	v_add_f32_e32 v171, v171, v156
	v_add_f32_e32 v220, v220, v157
	v_add_f32_e32 v171, v171, v158
	v_add_f32_e32 v220, v220, v159
	v_add_f32_e32 v171, v171, v160
	v_add_f32_e32 v220, v220, v161
	v_add_f32_e32 v171, v171, v162
	v_add_f32_e32 v220, v220, v163
	v_add_f32_e32 v171, v171, v164
	v_add_f32_e32 v220, v220, v165
	v_add_f32_e32 v171, v171, v166
	v_add_f32_e32 v220, v220, v167
	v_add_f32_e32 v171, v171, v168
	v_add_f32_e32 v220, v220, v169
	v_cvt_pk_bf16_f32 v106, v154, v155
	v_cvt_pk_bf16_f32 v107, v156, v157
	v_cvt_pk_bf16_f32 v108, v158, v159
	v_cvt_pk_bf16_f32 v109, v160, v161
	v_cvt_pk_bf16_f32 v110, v162, v163
	v_cvt_pk_bf16_f32 v111, v164, v165
	v_cvt_pk_bf16_f32 v112, v166, v167
	v_cvt_pk_bf16_f32 v113, v168, v169
	s_waitcnt lgkmcnt(6)
	v_mfma_f32_32x32x16_bf16 v[18:33], v[204:207], v[98:101], v[18:33]
	s_waitcnt lgkmcnt(4)
	v_mfma_f32_32x32x16_bf16 v[18:33], v[208:211], v[102:105], v[18:33]
	s_waitcnt lgkmcnt(2)
	v_mfma_f32_32x32x16_bf16 v[2:17], v[212:215], v[98:101], v[2:17]
	s_waitcnt lgkmcnt(0)
	v_mfma_f32_32x32x16_bf16 v[2:17], v[216:219], v[102:105], v[2:17]
	v_add_u32_e32 v222, 13824, v153
	ds_read_b64_tr_b16 v[154:155], v222 offset:55296
	ds_read_b64_tr_b16 v[156:157], v222 offset:56448
	ds_read_b64_tr_b16 v[158:159], v222 offset:57600
	ds_read_b64_tr_b16 v[160:161], v222 offset:58752
	ds_read_b64_tr_b16 v[162:163], v222 offset:55360
	ds_read_b64_tr_b16 v[164:165], v222 offset:56512
	ds_read_b64_tr_b16 v[166:167], v222 offset:57664
	ds_read_b64_tr_b16 v[168:169], v222 offset:58816
	v_sub_f32_e32 v34, v34, v170
	v_sub_f32_e32 v35, v35, v170
	v_sub_f32_e32 v36, v36, v170
	v_sub_f32_e32 v37, v37, v170
	v_sub_f32_e32 v38, v38, v170
	v_sub_f32_e32 v39, v39, v170
	v_sub_f32_e32 v40, v40, v170
	v_sub_f32_e32 v41, v41, v170
	v_sub_f32_e32 v42, v42, v170
	v_sub_f32_e32 v43, v43, v170
	v_sub_f32_e32 v44, v44, v170
	v_sub_f32_e32 v45, v45, v170
	v_sub_f32_e32 v46, v46, v170
	v_sub_f32_e32 v47, v47, v170
	v_sub_f32_e32 v48, v48, v170
	v_sub_f32_e32 v49, v49, v170
	v_exp_f32_e32 v34, v34
	v_exp_f32_e32 v35, v35
	v_exp_f32_e32 v36, v36
	v_exp_f32_e32 v37, v37
	v_exp_f32_e32 v38, v38
	v_exp_f32_e32 v39, v39
	v_exp_f32_e32 v40, v40
	v_exp_f32_e32 v41, v41
	v_exp_f32_e32 v42, v42
	v_exp_f32_e32 v43, v43
	v_exp_f32_e32 v44, v44
	v_exp_f32_e32 v45, v45
	v_exp_f32_e32 v46, v46
	v_exp_f32_e32 v47, v47
	v_exp_f32_e32 v48, v48
	v_exp_f32_e32 v49, v49
	v_add_f32_e32 v171, v171, v34
	v_add_f32_e32 v220, v220, v35
	v_add_f32_e32 v171, v171, v36
	v_add_f32_e32 v220, v220, v37
	v_add_f32_e32 v171, v171, v38
	v_add_f32_e32 v220, v220, v39
	v_add_f32_e32 v171, v171, v40
	v_add_f32_e32 v220, v220, v41
	v_add_f32_e32 v171, v171, v42
	v_add_f32_e32 v220, v220, v43
	v_add_f32_e32 v171, v171, v44
	v_add_f32_e32 v220, v220, v45
	v_add_f32_e32 v171, v171, v46
	v_add_f32_e32 v220, v220, v47
	v_add_f32_e32 v171, v171, v48
	v_add_f32_e32 v220, v220, v49
	v_cvt_pk_bf16_f32 v98, v34, v35
	v_cvt_pk_bf16_f32 v99, v36, v37
	v_cvt_pk_bf16_f32 v100, v38, v39
	v_cvt_pk_bf16_f32 v101, v40, v41
	v_cvt_pk_bf16_f32 v102, v42, v43
	v_cvt_pk_bf16_f32 v103, v44, v45
	v_cvt_pk_bf16_f32 v104, v46, v47
	v_cvt_pk_bf16_f32 v105, v48, v49
	s_waitcnt lgkmcnt(6)
; #define MFMA32(a, b, c) __builtin_amdgcn_mfma_f32_32x32x16_bf16((a), (b), (c), 0, 0, 0)
; DI unsigned cvtpk(float lo, float hi) { f32x2_t v = {lo, hi}; bf16x2_t b = __builtin_convertvector(v, bf16x2_t); return __builtin_bit_cast(unsigned, b); }
; DI void dil_compute(LAS char* lds, const DilU& u, const LAS float* tbl, int tid, const bf16x8 (&qf)[4]) {
;     ...
;         for (int db = 0; db < 2; ++db) {
;             const bf16x8 v0 = frag_tr_perm(Vt, DIL_PITCH, 0, 32 * db, lane), v1 = frag_tr_perm(Vt, DIL_PITCH, 16, 32 * db, lane);
;             o[db] = MFMA32(v0, pb0, o[db]); o[db] = MFMA32(v1, pb1, o[db]);
;         }
;     }
;     l += __shfl_xor(l, 32);
;     const float inv = 1.f / l;
;     bf16* orow = u.Ob + (long)(32 * w + r32) * u.ostride;
; #pragma unroll
;     for (int db = 0; db < 2; ++db)
; #pragma unroll
;         for (int g = 0; g < 4; ++g) { u32x2 wv; wv.x = cvtpk(o[db][4 * g] * inv, o[db][4 * g + 1] * inv); wv.y = cvtpk(o[db][4 * g + 2] * inv, o[db][4 * g + 3] * inv);
;             *(u32x2*)(orow + 32 * db + 8 * g + 4 * hi) = wv; }
;     if (hi == 0) u.lse[(long)(32 * w + r32) * u.lstride] = m + __log2f(l);
	v_mfma_f32_32x32x16_bf16 v[18:33], v[154:157], v[106:109], v[18:33]
	s_waitcnt lgkmcnt(4)
	v_mfma_f32_32x32x16_bf16 v[18:33], v[158:161], v[110:113], v[18:33]
	s_waitcnt lgkmcnt(2)
	v_mfma_f32_32x32x16_bf16 v[2:17], v[162:165], v[106:109], v[2:17]
	s_waitcnt lgkmcnt(0)
	v_mfma_f32_32x32x16_bf16 v[2:17], v[166:169], v[110:113], v[2:17]
	v_add_u32_e32 v222, 18432, v153
	ds_read_b64_tr_b16 v[34:35], v222 offset:55296
	ds_read_b64_tr_b16 v[36:37], v222 offset:56448
	ds_read_b64_tr_b16 v[38:39], v222 offset:57600
	ds_read_b64_tr_b16 v[40:41], v222 offset:58752
	ds_read_b64_tr_b16 v[42:43], v222 offset:55360
	ds_read_b64_tr_b16 v[44:45], v222 offset:56512
	ds_read_b64_tr_b16 v[46:47], v222 offset:57664
	ds_read_b64_tr_b16 v[48:49], v222 offset:58816
	s_waitcnt lgkmcnt(6)
	v_mfma_f32_32x32x16_bf16 v[18:33], v[34:37], v[98:101], v[18:33]
	s_waitcnt lgkmcnt(4)
	v_mfma_f32_32x32x16_bf16 v[18:33], v[38:41], v[102:105], v[18:33]
	s_waitcnt lgkmcnt(2)
	v_mfma_f32_32x32x16_bf16 v[2:17], v[42:45], v[98:101], v[2:17]
	s_waitcnt lgkmcnt(0)
	v_mfma_f32_32x32x16_bf16 v[2:17], v[46:49], v[102:105], v[2:17]
	v_add_f32_e32 v174, v171, v220
	v_or_b32_e32 v172, s10, v131
	ds_bpermute_b32 v173, v133, v174
	v_mov_b32_e32 v147, 0
	v_mul_lo_u32 v178, v172, s6
	v_mov_b32_e32 v179, 0
	v_lshl_add_u64 v[178:179], v[178:179], 1, s[12:13]
	v_lshl_add_u64 v[178:179], v[178:179], 0, v[146:147]
	s_waitcnt lgkmcnt(0)
	v_add_f32_e32 v174, v174, v173
	v_div_scale_f32 v175, s[10:11], v174, v174, 1.0
	v_rcp_f32_e32 v176, v175
	v_div_scale_f32 v177, vcc, 1.0, v174, 1.0
	v_fma_f32 v180, -v175, v176, 1.0
	v_fmac_f32_e32 v176, v180, v176
	v_mul_f32_e32 v180, v177, v176
	v_fma_f32 v181, -v175, v180, v177
	v_fmac_f32_e32 v180, v181, v176
	v_fma_f32 v175, -v175, v180, v177
	v_div_fmas_f32 v175, v175, v176, v180
	v_div_fixup_f32 v176, v175, v174, 1.0
	s_nop 0
	v_lshl_add_u64 v[178:179], v[178:179], 0, v[146:147]
	v_mul_f32_e32 v18, v18, v176
	v_mul_f32_e32 v19, v19, v176
	v_mul_f32_e32 v20, v20, v176
	v_mul_f32_e32 v21, v21, v176
	v_mul_f32_e32 v22, v22, v176
	v_mul_f32_e32 v23, v23, v176
	v_mul_f32_e32 v24, v24, v176
	v_mul_f32_e32 v25, v25, v176
	v_cvt_pk_bf16_f32 v18, v18, v19
	v_cvt_pk_bf16_f32 v19, v20, v21
	v_cvt_pk_bf16_f32 v20, v22, v23
	v_cvt_pk_bf16_f32 v21, v24, v25
	v_mul_f32_e32 v26, v26, v176
	v_mul_f32_e32 v27, v27, v176
	v_mul_f32_e32 v28, v28, v176
	v_mul_f32_e32 v29, v29, v176
	v_mul_f32_e32 v30, v30, v176
	v_mul_f32_e32 v31, v31, v176
	v_mul_f32_e32 v32, v32, v176
	v_mul_f32_e32 v33, v33, v176
	v_cvt_pk_bf16_f32 v26, v26, v27
	v_cvt_pk_bf16_f32 v27, v28, v29
	v_cvt_pk_bf16_f32 v28, v30, v31
	v_cvt_pk_bf16_f32 v29, v32, v33
	v_mul_f32_e32 v2, v2, v176
	v_mul_f32_e32 v3, v3, v176
	v_mul_f32_e32 v4, v4, v176
	v_mul_f32_e32 v5, v5, v176
	v_mul_f32_e32 v6, v6, v176
	v_mul_f32_e32 v7, v7, v176
	v_mul_f32_e32 v8, v8, v176
	v_mul_f32_e32 v9, v9, v176
	v_cvt_pk_bf16_f32 v2, v2, v3
	v_cvt_pk_bf16_f32 v3, v4, v5
	v_cvt_pk_bf16_f32 v4, v6, v7
	v_cvt_pk_bf16_f32 v5, v8, v9
	v_mul_f32_e32 v10, v10, v176
	v_mul_f32_e32 v11, v11, v176
	v_mul_f32_e32 v12, v12, v176
	v_mul_f32_e32 v13, v13, v176
	v_mul_f32_e32 v14, v14, v176
	v_mul_f32_e32 v15, v15, v176
	v_mul_f32_e32 v16, v16, v176
	v_mul_f32_e32 v17, v17, v176
	v_cvt_pk_bf16_f32 v10, v10, v11
	v_cvt_pk_bf16_f32 v11, v12, v13
	v_cvt_pk_bf16_f32 v12, v14, v15
	v_cvt_pk_bf16_f32 v13, v16, v17
	s_nop 1
	v_permlane32_swap_b32_e32 v18, v20
	v_permlane32_swap_b32_e32 v19, v21
	v_permlane32_swap_b32_e32 v26, v28
	v_permlane32_swap_b32_e32 v27, v29
	v_permlane32_swap_b32_e32 v2, v4
	v_permlane32_swap_b32_e32 v3, v5
	v_permlane32_swap_b32_e32 v10, v12
	v_permlane32_swap_b32_e32 v11, v13
	s_nop 1
	global_store_dwordx4 v[178:179], v[18:21], off
	global_store_dwordx4 v[178:179], v[26:29], off offset:32
	global_store_dwordx4 v[178:179], v[2:5], off offset:64
	global_store_dwordx4 v[178:179], v[10:13], off offset:96
	s_and_saveexec_b64 s[10:11], s[40:41]
	s_cbranch_execz .LBB0_521
	v_log_f32_e32 v182, v174
	v_mul_lo_u32 v180, v172, s5
	v_mov_b32_e32 v181, 0
	v_lshl_add_u64 v[180:181], v[180:181], 2, s[8:9]
	v_add_f32_e32 v182, v145, v182
	global_store_dword v[180:181], v182, off
	s_branch .LBB0_521
